# gla_c: next unit's glow / decay-projection / bias fragment loads issued at the start of the current unit's epilogue into spare registers; the unit top only moves them into place
# baseline (speedup 1.0000x reference)
.LBB0_816:
	s_cmp_lt_i32 s56, 6
	s_cselect_b64 s[2:3], -1, 0
	s_and_b64 s[66:67], s[2:3], s[0:1]
	s_andn2_b64 vcc, exec, s[66:67]
	s_cbranch_vccnz .LBB0_856
	s_cmpk_lt_i32 s33, 0x800
	v_and_b32_e32 v84, 15, v145
	v_lshrrev_b32_e32 v35, 7, v145
	v_lshrrev_b32_e32 v85, 3, v145
	s_cbranch_scc0 .LBB0_832
	s_add_u32 s68, s54, 0x6800000
	s_waitcnt lgkmcnt(0)
	v_lshrrev_b32_e32 v1, 4, v144
	v_readlane_b32 s45, v244, 6
	s_addc_u32 s69, s55, 0
	v_lshlrev_b32_e32 v0, 3, v1
	s_lshr_b32 s0, s45, 8
	v_readlane_b32 s44, v244, 25
	v_lshrrev_b32_e32 v2, 5, v144
	s_lshl_b32 s1, s44, 5
	v_cmp_eq_u32_e64 s[2:3], s0, v2
	v_lshlrev_b32_e32 v1, 2, v1
	v_and_b32_e32 v2, 8, v0
	v_mov_b32_e32 v31, 0
	s_lshl_b32 s78, s0, 9
	v_lshl_or_b32 v4, s0, 6, v1
	v_lshl_or_b32 v30, s0, 4, v2
	s_and_b32 s0, s1, 0x60
	v_lshlrev_b64 v[2:3], 11, v[30:31]
	v_or_b32_e32 v34, s0, v84
	s_movk_i32 s0, 0x204
	v_lshl_add_u64 v[32:33], s[88:89], 0, v[2:3]
	v_mul_lo_u32 v7, v4, s0
	v_and_b32_e32 v2, 0x7f, v145
	v_and_b32_e32 v4, 1, v35
	v_mul_u32_u24_e32 v6, 0x8100, v4
	v_lshlrev_b32_e32 v2, 2, v2
	v_add3_u32 v8, 0, v6, v2
	v_cmp_eq_u32_e64 s[4:5], 0, v4
	v_cmp_eq_u32_e64 s[6:7], 1, v4
	v_and_b32_e32 v6, 0x300, v145
	v_lshlrev_b32_e32 v4, 7, v4
	v_sub_u32_e32 v4, v4, v6
	v_lshlrev_b32_e32 v4, 2, v4
	s_add_i32 s8, 0, 0x10600
	s_add_i32 s12, 0, 0x10200
	v_lshrrev_b32_e32 v5, 8, v145
	v_add3_u32 v88, s8, v4, v2
	v_lshl_add_u32 v89, v145, 2, s12
	v_and_b32_e32 v2, 0x78, v85
	v_mad_u32_u24 v4, v144, s0, 0
	v_or_b32_e32 v6, 7, v85
	s_lshl_b32 s12, s44, 3
	v_mul_u32_u24_e32 v9, 0x4080, v5
	v_cmp_eq_u32_e64 s[8:9], 1, v5
	v_mul_u32_u24_e32 v5, 0x110, v144
	s_add_i32 s42, 0, 0x12800
	v_lshl_add_u32 v90, v2, 2, v4
	v_lshl_add_u32 v91, v6, 2, v4
	v_lshlrev_b32_e32 v4, 1, v2
	s_and_b32 s12, s12, 0x1ffffff0
	s_movk_i32 s0, 0x110
	v_add3_u32 v92, s42, v5, v4
	v_or_b32_e32 v4, s12, v84
	v_mul_lo_u32 v4, v4, s0
	v_and_b32_e32 v5, 48, v144
	s_add_i32 s13, s12, 0x80
	v_add3_u32 v93, s42, v4, v5
	v_or_b32_e32 v4, s13, v84
	v_mul_lo_u32 v4, v4, s0
	v_mul_u32_u24_e32 v12, 0x90, v6
	v_add3_u32 v94, s42, v4, v5
	v_or_b32_e32 v4, s12, v1
	v_and_or_b32 v6, s1, 32, v84
	v_mul_u32_u24_e32 v13, 0x110, v6
	v_or_b32_e32 v15, 1, v4
	v_or_b32_e32 v16, 2, v4
	v_or_b32_e32 v17, 3, v4
	s_bfe_u32 s0, s45, 0x20006
	s_lshl_b32 s1, s44, 4
	s_movk_i32 s43, 0x90
	v_add3_u32 v95, s42, v13, v5
	v_lshl_add_u32 v13, v6, 1, 0
	v_cmp_gt_u32_e64 s[12:13], v6, v4
	v_cmp_lt_u32_e64 s[14:15], v6, v4
	v_cmp_gt_u32_e64 s[16:17], v6, v15
	v_cmp_gt_u32_e64 s[18:19], v6, v16
	v_cmp_lt_u32_e64 s[20:21], v6, v16
	v_cmp_gt_u32_e64 s[22:23], v6, v17
	v_cmp_lt_u32_e64 s[24:25], v6, v17
	v_or_b32_e32 v6, 16, v6
	v_lshl_or_b32 v97, s0, 4, v84
	s_and_b32 s44, s1, 0x3fffffc0
	v_mul_lo_u32 v14, v4, s43
	v_cmp_gt_u32_e64 s[26:27], v6, v4
	v_cmp_lt_u32_e64 s[28:29], v6, v4
	v_mul_u32_u24_e32 v4, 0x110, v97
	v_or_b32_e32 v30, s44, v84
	v_add3_u32 v98, s42, v4, v5
	v_or_b32_e32 v4, 16, v30
	v_mov_b32_e32 v5, v31
	v_cmp_gt_u32_e64 s[30:31], v6, v15
	v_cmp_gt_u32_e64 s[34:35], v6, v16
	v_cmp_lt_u32_e64 s[36:37], v6, v16
	v_cmp_gt_u32_e64 s[38:39], v6, v17
	v_cmp_lt_u32_e64 s[40:41], v6, v17
	v_lshlrev_b64 v[38:39], 8, v[4:5]
	v_or_b32_e32 v4, s44, v1
	v_or3_b32 v6, v1, s1, 48
	v_mbcnt_lo_u32_b32 v1, -1, 0
	v_mbcnt_hi_u32_b32 v1, -1, v1
	v_and_b32_e32 v20, 64, v1
	v_xor_b32_e32 v19, 16, v1
	v_add_u32_e32 v20, 64, v20
	v_cmp_lt_i32_e32 vcc, v19, v20
	v_mul_lo_u32 v18, v30, s43
	v_lshlrev_b64 v[36:37], 8, v[30:31]
	v_or_b32_e32 v30, 32, v30
	s_lshl_b32 s0, s0, 6
	v_cndmask_b32_e32 v19, v1, v19, vcc
	v_lshlrev_b64 v[40:41], 8, v[30:31]
	v_or3_b32 v30, v144, s1, 48
	s_and_b32 s45, s45, 0xffffff00
	s_add_i32 s0, s0, 0
	v_lshlrev_b32_e32 v101, 2, v19
	v_xor_b32_e32 v19, 32, v1
	v_and_b32_e32 v16, 48, v145
	v_mul_lo_u32 v5, v30, s43
	v_lshlrev_b64 v[42:43], 8, v[30:31]
	s_add_i32 s45, s0, s45
	v_lshlrev_b32_e32 v30, 2, v4
	v_cmp_lt_i32_e32 vcc, v19, v20
	v_lshl_add_u32 v3, v34, 2, 0
	s_movk_i32 s10, 0x100
	v_lshl_add_u32 v10, v144, 1, 0
	v_mul_u32_u24_e32 v11, 0x90, v2
	v_mad_u32_u24 v15, v97, s43, 0
	v_add_u32_e32 v17, 0, v16
	s_add_u32 s72, s54, 0x4400000
	v_lshl_add_u64 v[44:45], s[92:93], 0, v[30:31]
	v_lshlrev_b32_e32 v30, 2, v6
	v_cndmask_b32_e32 v1, v1, v19, vcc
	s_mov_b32 s71, 0
	v_or_b32_e32 v86, 0x80, v145
	v_and_b32_e32 v87, 0x37f, v145
	v_cmp_gt_u32_e64 s[10:11], s10, v145
	v_add_u32_e32 v96, 0x1100, v95
	v_cmp_gt_u32_e64 s[42:43], 16, v144
	v_lshl_add_u32 v99, v144, 2, s45
	v_lshl_add_u32 v100, v84, 2, s0
	s_addc_u32 s73, s55, 0
	v_lshl_add_u64 v[46:47], s[92:93], 0, v[30:31]
	v_lshlrev_b32_e32 v102, 2, v1
	s_movk_i32 s79, 0x2600
	s_mov_b32 s80, 0xbfb8aa3b
	s_mov_b32 s81, 0x800000
	s_mov_b32 s82, 0x3f317217
	s_mov_b32 s83, 0x7f800000
	v_lshlrev_b32_e32 v48, 1, v2
	s_mov_b32 s74, 0x3db504f3
	v_add_u32_e32 v103, v10, v11
	v_add_u32_e32 v104, v10, v12
	v_add_u32_e32 v105, v13, v14
	v_add_u32_e32 v106, v15, v16
	v_lshlrev_b32_e32 v30, 1, v0
	v_add_u32_e32 v107, v17, v18
	v_add_u32_e32 v108, v17, v5
	v_mov_b32_e32 v109, 0x358637bd
	s_mov_b64 s[76:77], 0x1140
	v_lshlrev_b32_e32 v50, 1, v4
	v_lshlrev_b32_e32 v52, 1, v6
	v_mov_b32_e32 v110, 0x41b17218
	v_add_u32_e32 v111, v3, v7
	v_add_u32_e32 v112, v8, v9
	s_mov_b32 s84, s33
	global_load_dwordx4 v[212:215], v[44:45], off
	global_load_dwordx4 v[216:219], v[44:45], off offset:64
	global_load_dwordx4 v[220:223], v[44:45], off offset:128
	global_load_dwordx4 v[224:227], v[46:47], off
	s_waitcnt vmcnt(0)
	s_mov_b32 s98, s84
	s_ashr_i32 s99, s98, 8
	s_and_b32 s100, s98, 63
	s_lshl_b32 s99, s99, 12
	s_lshl_b32 s100, s100, 6
	s_or_b32 s99, s99, s100
	s_bfe_u32 s100, s98, 0x20006
	v_or_b32_e32 v186, s99, v84
	v_mul_u32_u24_e32 v187, 0x2600, v186
	v_add_u32_e32 v187, v187, v30
	v_add_u32_e32 v187, 0x1000, v187
	global_load_dwordx4 v[150:153], v187, s[68:69] offset:1344
	v_add_u32_e32 v188, 0x26000, v187
	global_load_dwordx4 v[154:157], v188, s[68:69] offset:1344
	v_add_u32_e32 v188, 0x4c000, v187
	global_load_dwordx4 v[158:161], v188, s[68:69] offset:1344
	v_add_u32_e32 v188, 0x72000, v187
	global_load_dwordx4 v[162:165], v188, s[68:69] offset:1344
	s_lshl_b32 s101, s100, 7
	s_or_b32 s101, s101, s78
	v_or_b32_e32 v189, s101, v34
	v_lshlrev_b32_e32 v189, 2, v189
	global_load_dword v210, v189, s[90:91]
	global_load_dword v211, v189, s[90:91] offset:64
	s_lshl_b32 s100, s100, 9
	s_mov_b32 s101, 0
	v_lshl_add_u64 v[190:191], v[32:33], 0, s[100:101]
	v_lshlrev_b32_e32 v188, 2, v34
	v_mov_b32_e32 v189, v31
	v_lshl_add_u64 v[190:191], v[190:191], 0, v[188:189]
	s_and_saveexec_b64 s[100:101], s[2:3]
	global_load_dword v166, v[190:191], off
	global_load_dword v167, v[190:191], off offset:2048
	global_load_dword v200, v[190:191], off offset:64
	global_load_dword v201, v[190:191], off offset:2112
	v_add_co_u32_e32 v190, vcc, 0x1000, v190
	s_nop 1
	v_addc_co_u32_e32 v191, vcc, 0, v191, vcc
	global_load_dword v168, v[190:191], off
	global_load_dword v169, v[190:191], off offset:2048
	global_load_dword v202, v[190:191], off offset:64
	global_load_dword v203, v[190:191], off offset:2112
	v_add_co_u32_e32 v190, vcc, 0x1000, v190
	s_nop 1
	v_addc_co_u32_e32 v191, vcc, 0, v191, vcc
	global_load_dword v170, v[190:191], off
	global_load_dword v171, v[190:191], off offset:2048
	global_load_dword v204, v[190:191], off offset:64
	global_load_dword v205, v[190:191], off offset:2112
	v_add_co_u32_e32 v190, vcc, 0x1000, v190
	s_nop 1
	v_addc_co_u32_e32 v191, vcc, 0, v191, vcc
	global_load_dword v172, v[190:191], off
	global_load_dword v173, v[190:191], off offset:2048
	global_load_dword v206, v[190:191], off offset:64
	global_load_dword v207, v[190:191], off offset:2112
	s_or_b64 exec, exec, s[100:101]
	s_waitcnt vmcnt(0)
	s_branch .LBB0_820
.LBB0_819:
	s_or_b64 exec, exec, s[0:1]
	v_readlane_b32 s98, v244, 4
	s_nop 1
	s_add_i32 s98, s84, s98
	s_cmpk_gt_i32 s98, 0x7ff
	s_cbranch_scc1 .Lglc_nopf
	s_ashr_i32 s99, s98, 8
	s_and_b32 s100, s98, 63
	s_lshl_b32 s99, s99, 12
	s_lshl_b32 s100, s100, 6
	s_or_b32 s99, s99, s100
	s_bfe_u32 s100, s98, 0x20006
	v_or_b32_e32 v186, s99, v84
	v_mul_u32_u24_e32 v187, 0x2600, v186
	v_add_u32_e32 v187, v187, v30
	v_add_u32_e32 v187, 0x1000, v187
	global_load_dwordx4 v[150:153], v187, s[68:69] offset:1344
	v_add_u32_e32 v188, 0x26000, v187
	global_load_dwordx4 v[154:157], v188, s[68:69] offset:1344
	v_add_u32_e32 v188, 0x4c000, v187
	global_load_dwordx4 v[158:161], v188, s[68:69] offset:1344
	v_add_u32_e32 v188, 0x72000, v187
	global_load_dwordx4 v[162:165], v188, s[68:69] offset:1344
	s_lshl_b32 s101, s100, 7
	s_or_b32 s101, s101, s78
	v_or_b32_e32 v189, s101, v34
	v_lshlrev_b32_e32 v189, 2, v189
	global_load_dword v210, v189, s[90:91]
	global_load_dword v211, v189, s[90:91] offset:64
	s_lshl_b32 s100, s100, 9
	s_mov_b32 s101, 0
	v_lshl_add_u64 v[190:191], v[32:33], 0, s[100:101]
	v_lshlrev_b32_e32 v188, 2, v34
	v_mov_b32_e32 v189, v31
	v_lshl_add_u64 v[190:191], v[190:191], 0, v[188:189]
	s_and_saveexec_b64 s[100:101], s[2:3]
	global_load_dword v166, v[190:191], off
	global_load_dword v167, v[190:191], off offset:2048
	global_load_dword v200, v[190:191], off offset:64
	global_load_dword v201, v[190:191], off offset:2112
	v_add_co_u32_e32 v190, vcc, 0x1000, v190
	s_nop 1
	v_addc_co_u32_e32 v191, vcc, 0, v191, vcc
	global_load_dword v168, v[190:191], off
	global_load_dword v169, v[190:191], off offset:2048
	global_load_dword v202, v[190:191], off offset:64
	global_load_dword v203, v[190:191], off offset:2112
	v_add_co_u32_e32 v190, vcc, 0x1000, v190
	s_nop 1
	v_addc_co_u32_e32 v191, vcc, 0, v191, vcc
	global_load_dword v170, v[190:191], off
	global_load_dword v171, v[190:191], off offset:2048
	global_load_dword v204, v[190:191], off offset:64
	global_load_dword v205, v[190:191], off offset:2112
	v_add_co_u32_e32 v190, vcc, 0x1000, v190
	s_nop 1
	v_addc_co_u32_e32 v191, vcc, 0, v191, vcc
	global_load_dword v172, v[190:191], off
	global_load_dword v173, v[190:191], off offset:2048
	global_load_dword v206, v[190:191], off offset:64
	global_load_dword v207, v[190:191], off offset:2112
	s_or_b64 exec, exec, s[100:101]
.Lglc_nopf:
	v_or_b32_e32 v16, s44, v97
	v_mov_b64_e32 v[18:19], s[68:69]
	v_mad_i64_i32 v[18:19], s[0:1], v16, s79, v[18:19]
	v_lshl_add_u64 v[18:19], v[18:19], 0, s[70:71]
	v_lshl_add_u64 v[20:21], v[18:19], 0, s[76:77]
	v_mov_b32_e32 v230, v52
	v_mov_b32_e32 v231, v31
	v_lshl_add_u64 v[230:231], v[20:21], 0, v[230:231]
	v_mov_b32_e32 v51, v31
	v_lshl_add_u64 v[24:25], v[20:21], 0, v[50:51]
	s_waitcnt lgkmcnt(0)
	s_barrier
	v_mov_b32_e32 v54, v176
	v_mov_b32_e32 v55, v177
	ds_read2st64_b32 v[18:19], v100 offset0:108 offset1:109
	v_ashrrev_i32_e32 v17, 31, v16
	v_lshlrev_b64 v[16:17], 10, v[16:17]
	v_lshl_add_u64 v[16:17], s[72:73], 0, v[16:17]
	v_lshl_add_u64 v[16:17], v[16:17], 0, s[70:71]
	s_waitcnt lgkmcnt(0)
	v_add_f32_e32 v18, v18, v19
	v_fmamk_f32 v18, v18, 0x3c000000, v109
	v_rsq_f32_e32 v18, v18
	v_lshl_add_u64 v[22:23], v[16:17], 0, v[50:51]
	v_mov_b32_e32 v56, v178
	v_mov_b32_e32 v57, v179
	v_mov_b32_e32 v24, v180
	v_mov_b32_e32 v25, v181
	v_mov_b32_e32 v228, v182
	v_mov_b32_e32 v229, v183
	v_pk_mul_f32 v[12:13], v[12:13], v[18:19] op_sel_hi:[1,0]
	v_pk_mul_f32 v[14:15], v[14:15], v[18:19] op_sel_hi:[1,0]
	v_lshlrev_b32_e32 v58, 16, v54
	v_and_b32_e32 v59, 0xffff0000, v54
	v_mul_f32_e32 v19, 0xbfb8aa3b, v58
	v_mul_f32_e32 v49, 0xbfb8aa3b, v59
	v_lshlrev_b32_e32 v54, 16, v55
	v_and_b32_e32 v55, 0xffff0000, v55
	v_exp_f32_e32 v60, v19
	v_exp_f32_e32 v61, v49
	v_mul_f32_e32 v51, 0xbfb8aa3b, v54
	v_mul_f32_e32 v53, 0xbfb8aa3b, v55
	v_exp_f32_e32 v62, v51
	v_exp_f32_e32 v63, v53
	v_pk_mul_f32 v[12:13], v[212:213], v[12:13]
	v_pk_add_f32 v[26:27], v[60:61], 1.0 op_sel_hi:[1,0]
	v_pk_mul_f32 v[14:15], v[214:215], v[14:15]
	v_pk_add_f32 v[28:29], v[62:63], 1.0 op_sel_hi:[1,0]
	s_mov_b64 vcc, s[0:1]
	v_rcp_f32_e32 v27, v27
	s_mov_b64 vcc, s[46:47]
	v_rcp_f32_e32 v26, v26
	s_mov_b64 vcc, s[48:49]
	v_rcp_f32_e32 v29, v29
	v_pk_mul_f32 v[26:27], v[26:27], v[58:59]
	v_rcp_f32_e32 v28, v28
	v_pk_mul_f32 v[12:13], v[12:13], v[26:27]
	v_pk_mul_f32 v[26:27], v[28:29], v[54:55]
	v_cvt_pk_bf16_f32 v12, v12, v13
	v_pk_mul_f32 v[14:15], v[14:15], v[26:27]
	v_lshlrev_b32_e32 v26, 16, v56
	v_cvt_pk_bf16_f32 v13, v14, v15
	global_store_dwordx2 v[22:23], v[12:13], off
	v_and_b32_e32 v27, 0xffff0000, v56
	v_mul_f32_e32 v19, 0xbfb8aa3b, v26
	v_mul_f32_e32 v49, 0xbfb8aa3b, v27
	v_lshlrev_b32_e32 v28, 16, v57
	v_and_b32_e32 v29, 0xffff0000, v57
	v_exp_f32_e32 v54, v19
	v_exp_f32_e32 v55, v49
	v_mul_f32_e32 v51, 0xbfb8aa3b, v28
	v_mul_f32_e32 v53, 0xbfb8aa3b, v29
	v_exp_f32_e32 v56, v51
	v_exp_f32_e32 v57, v53
	v_pk_add_f32 v[54:55], v[54:55], 1.0 op_sel_hi:[1,0]
	v_pk_mul_f32 v[8:9], v[8:9], v[18:19] op_sel_hi:[1,0]
	v_pk_mul_f32 v[10:11], v[10:11], v[18:19] op_sel_hi:[1,0]
	v_pk_add_f32 v[56:57], v[56:57], 1.0 op_sel_hi:[1,0]
	s_mov_b64 vcc, s[0:1]
	v_rcp_f32_e32 v55, v55
	s_mov_b64 vcc, s[46:47]
	v_rcp_f32_e32 v54, v54
	s_mov_b64 vcc, s[48:49]
	v_pk_mul_f32 v[26:27], v[54:55], v[26:27]
	v_rcp_f32_e32 v55, v57
	s_nop 0
	v_rcp_f32_e32 v54, v56
	s_nop 0
	v_pk_mul_f32 v[28:29], v[54:55], v[28:29]
	v_mov_b32_e32 v53, v31
	v_pk_mul_f32 v[8:9], v[216:217], v[8:9]
	v_pk_mul_f32 v[10:11], v[218:219], v[10:11]
	v_pk_mul_f32 v[8:9], v[8:9], v[26:27]
	v_pk_mul_f32 v[10:11], v[10:11], v[28:29]
	v_cvt_pk_bf16_f32 v8, v8, v9
	v_cvt_pk_bf16_f32 v9, v10, v11
	global_store_dwordx2 v[22:23], v[8:9], off offset:32
	v_lshlrev_b32_e32 v14, 16, v24
	v_and_b32_e32 v15, 0xffff0000, v24
	v_lshl_add_u64 v[12:13], v[20:21], 0, v[52:53]
	v_lshlrev_b32_e32 v20, 16, v25
	v_and_b32_e32 v21, 0xffff0000, v25
	v_mul_f32_e32 v19, 0xbfb8aa3b, v14
	v_mul_f32_e32 v25, 0xbfb8aa3b, v15
	v_exp_f32_e32 v24, v19
	v_exp_f32_e32 v25, v25
	v_mul_f32_e32 v26, 0xbfb8aa3b, v20
	v_mul_f32_e32 v27, 0xbfb8aa3b, v21
	v_exp_f32_e32 v26, v26
	v_exp_f32_e32 v27, v27
	v_pk_add_f32 v[24:25], v[24:25], 1.0 op_sel_hi:[1,0]
	v_pk_mul_f32 v[4:5], v[4:5], v[18:19] op_sel_hi:[1,0]
	v_pk_mul_f32 v[6:7], v[6:7], v[18:19] op_sel_hi:[1,0]
	v_pk_add_f32 v[26:27], v[26:27], 1.0 op_sel_hi:[1,0]
	v_div_scale_f32 v55, s[44:45], v26, v26, 1.0
	v_rcp_f32_e32 v60, v55
	s_nop 0
	v_fma_f32 v64, -v55, v60, 1.0
	v_div_scale_f32 v56, s[48:49], 1.0, v26, 1.0
	v_fmac_f32_e32 v60, v64, v60
	v_mul_f32_e32 v64, v56, v60
	v_fma_f32 v68, -v55, v64, v56
	s_mov_b64 vcc, s[0:1]
	v_fmac_f32_e32 v64, v68, v60
	v_rcp_f32_e32 v25, v25
	s_mov_b64 vcc, s[46:47]
	v_fma_f32 v49, -v55, v64, v56
	v_rcp_f32_e32 v24, v24
	s_mov_b64 vcc, s[48:49]
	v_pk_mul_f32 v[14:15], v[24:25], v[14:15]
	v_rcp_f32_e32 v25, v27
	v_div_fmas_f32 v19, v49, v60, v64
	v_div_fixup_f32 v24, v19, v26, 1.0
	v_pk_mul_f32 v[20:21], v[24:25], v[20:21]
	v_readlane_b32 s0, v244, 4
	v_pk_mul_f32 v[0:1], v[0:1], v[18:19] op_sel_hi:[1,0]
	v_readlane_b32 s1, v244, 5
	s_add_i32 s84, s84, s0
	v_pk_mul_f32 v[2:3], v[2:3], v[18:19] op_sel_hi:[1,0]
	v_pk_mul_f32 v[4:5], v[4:5], v[220:221]
	v_pk_mul_f32 v[6:7], v[6:7], v[222:223]
	v_pk_mul_f32 v[4:5], v[4:5], v[14:15]
	v_pk_mul_f32 v[6:7], v[6:7], v[20:21]
	v_cvt_pk_bf16_f32 v4, v4, v5
	v_cvt_pk_bf16_f32 v5, v6, v7
	global_store_dwordx2 v[22:23], v[4:5], off offset:64
	v_lshl_add_u64 v[10:11], v[16:17], 0, v[52:53]
	s_cmpk_gt_i32 s84, 0x7ff
	v_lshlrev_b32_e32 v12, 16, v228
	v_and_b32_e32 v13, 0xffff0000, v228
	v_mul_f32_e32 v14, 0xbfb8aa3b, v12
	v_mul_f32_e32 v15, 0xbfb8aa3b, v13
	v_lshlrev_b32_e32 v8, 16, v229
	v_and_b32_e32 v9, 0xffff0000, v229
	v_exp_f32_e32 v14, v14
	v_exp_f32_e32 v15, v15
	v_mul_f32_e32 v16, 0xbfb8aa3b, v8
	v_mul_f32_e32 v17, 0xbfb8aa3b, v9
	v_exp_f32_e32 v16, v16
	v_exp_f32_e32 v17, v17
	v_pk_mul_f32 v[0:1], v[0:1], v[224:225]
	v_pk_add_f32 v[4:5], v[14:15], 1.0 op_sel_hi:[1,0]
	v_pk_mul_f32 v[2:3], v[2:3], v[226:227]
	v_pk_add_f32 v[6:7], v[16:17], 1.0 op_sel_hi:[1,0]
	s_mov_b64 vcc, s[0:1]
	v_rcp_f32_e32 v5, v5
	s_mov_b64 vcc, s[46:47]
	v_rcp_f32_e32 v4, v4
	s_mov_b64 vcc, s[48:49]
	v_pk_mul_f32 v[4:5], v[4:5], v[12:13]
	v_rcp_f32_e32 v7, v7
	s_nop 0
	v_rcp_f32_e32 v6, v6
	v_pk_mul_f32 v[0:1], v[0:1], v[4:5]
	v_pk_mul_f32 v[4:5], v[6:7], v[8:9]
	v_cvt_pk_bf16_f32 v0, v0, v1
	v_pk_mul_f32 v[2:3], v[2:3], v[4:5]
	s_nop 0
	v_cvt_pk_bf16_f32 v1, v2, v3
	global_store_dwordx2 v[10:11], v[0:1], off
	s_barrier
	s_cbranch_scc1 .LBB0_832
.LBB0_820:
	s_ashr_i32 s85, s84, 8
	s_and_b32 s45, s84, 63
	s_lshl_b32 s0, s85, 12
	s_lshl_b32 s1, s45, 6
	s_or_b32 s44, s0, s1
	v_or_b32_e32 v6, s44, v84
	v_mov_b64_e32 v[0:1], s[68:69]
	v_mad_i64_i32 v[2:3], s[0:1], v6, s79, v[0:1]
	v_lshl_add_u64 v[2:3], v[2:3], 0, v[30:31]
	v_or_b32_e32 v4, 16, v6
	v_add_co_u32_e32 v2, vcc, 0x1000, v2
	v_mad_i64_i32 v[4:5], s[0:1], v4, s79, v[0:1]
	s_nop 0
	v_addc_co_u32_e32 v3, vcc, 0, v3, vcc
	v_lshl_add_u64 v[4:5], v[4:5], 0, v[30:31]
	v_add_co_u32_e32 v4, vcc, 0x1000, v4
	s_bfe_u32 s86, s84, 0x20006
	s_nop 0
	v_addc_co_u32_e32 v5, vcc, 0, v5, vcc
	s_waitcnt vmcnt(4)
	v_mov_b32_e32 v12, v150
	v_mov_b32_e32 v13, v151
	v_mov_b32_e32 v14, v152
	v_mov_b32_e32 v15, v153
	v_mov_b32_e32 v8, v154
	v_mov_b32_e32 v9, v155
	v_mov_b32_e32 v10, v156
	v_mov_b32_e32 v11, v157
	v_or_b32_e32 v2, 32, v6
	v_mad_i64_i32 v[2:3], s[0:1], v2, s79, v[0:1]
	v_lshl_add_u64 v[2:3], v[2:3], 0, v[30:31]
	v_or_b32_e32 v4, 48, v6
	v_add_co_u32_e32 v2, vcc, 0x1000, v2
	v_mad_i64_i32 v[0:1], s[0:1], v4, s79, v[0:1]
	s_nop 0
	v_addc_co_u32_e32 v3, vcc, 0, v3, vcc
	v_lshl_add_u64 v[0:1], v[0:1], 0, v[30:31]
	v_add_co_u32_e32 v0, vcc, 0x1000, v0
	s_lshl_b32 s70, s86, 9
	s_nop 0
	v_addc_co_u32_e32 v1, vcc, 0, v1, vcc
	v_mov_b32_e32 v4, v158
	v_mov_b32_e32 v5, v159
	v_mov_b32_e32 v6, v160
	v_mov_b32_e32 v7, v161
	s_nop 0
	v_mov_b32_e32 v0, v162
	v_mov_b32_e32 v1, v163
	v_mov_b32_e32 v2, v164
	v_mov_b32_e32 v3, v165
	v_lshl_add_u64 v[20:21], v[32:33], 0, s[70:71]
	v_lshlrev_b32_e32 v22, 2, v34
	v_mov_b32_e32 v16, 0
	v_mov_b32_e32 v17, 0
	v_mov_b32_e32 v18, 0
	v_mov_b32_e32 v19, 0
	s_lshl_b32 s98, s86, 7
	s_or_b32 s98, s98, s78
	v_or_b32_e32 v208, s98, v34
	v_mov_b32_e32 v209, v31
	v_lshl_add_u64 v[208:209], v[208:209], 2, s[90:91]
	s_and_saveexec_b64 s[0:1], s[2:3]
	v_mov_b32_e32 v23, v31
	v_lshl_add_u64 v[16:17], v[20:21], 0, v[22:23]
	v_add_co_u32_e32 v18, vcc, 0x1000, v16
	s_nop 1
	v_addc_co_u32_e32 v19, vcc, 0, v17, vcc
	v_add_co_u32_e32 v24, vcc, 0x2000, v16
	s_nop 1
	v_addc_co_u32_e32 v25, vcc, 0, v17, vcc
	v_add_co_u32_e32 v26, vcc, 0x3000, v16
	s_nop 1
	v_addc_co_u32_e32 v27, vcc, 0, v17, vcc
	v_mov_b32_e32 v23, v166
	v_mov_b32_e32 v16, v167
	v_mov_b32_e32 v17, v168
	v_mov_b32_e32 v18, v169
	v_mov_b32_e32 v19, v170
	v_mov_b32_e32 v24, v171
	v_mov_b32_e32 v25, v172
	v_mov_b32_e32 v26, v173
	s_or_b64 exec, exec, s[0:1]
	v_or_b32_e32 v190, s44, v144
	v_mov_b64_e32 v[174:175], s[68:69]
	v_mad_i64_i32 v[174:175], vcc, v190, s79, v[174:175]
	s_lshl_b32 s100, s86, 8
	s_mov_b32 s101, 0
	v_lshl_add_u64 v[174:175], v[174:175], 0, s[100:101]
	v_mov_b32_e32 v190, v48
	v_mov_b32_e32 v191, v31
	v_lshl_add_u64 v[174:175], v[174:175], 0, v[190:191]
	global_load_dwordx4 v[150:153], v[174:175], off offset:1344
	global_load_dwordx4 v[154:157], v[174:175], off offset:2368
	global_load_dwordx4 v[158:161], v[174:175], off offset:1472
	global_load_dwordx4 v[162:165], v[174:175], off offset:2496
	global_load_dwordx4 v[166:169], v[174:175], off offset:3392
	global_load_dwordx4 v[170:173], v[174:175], off offset:3520
	v_or_b32_e32 v190, s44, v97
	v_mov_b64_e32 v[186:187], s[68:69]
	v_mad_i64_i32 v[186:187], vcc, v190, s79, v[186:187]
	v_lshl_add_u64 v[186:187], v[186:187], 0, s[100:101]
	v_lshl_add_u64 v[186:187], v[186:187], 0, s[76:77]
	v_mov_b32_e32 v190, v50
	v_lshl_add_u64 v[188:189], v[186:187], 0, v[190:191]
	v_mov_b32_e32 v190, v52
	v_lshl_add_u64 v[186:187], v[186:187], 0, v[190:191]
	global_load_dwordx2 v[176:177], v[188:189], off
	global_load_dwordx2 v[178:179], v[188:189], off offset:32
	global_load_dwordx2 v[180:181], v[188:189], off offset:64
	global_load_dwordx2 v[182:183], v[186:187], off
	s_lshl_b32 s98, s85, 3
	s_lshl_b32 s99, s86, 1
	s_or_b32 s98, s99, s98
	s_ashr_i32 s99, s98, 31
	s_lshl_b64 s[98:99], s[98:99], 21
	s_add_u32 s98, s98, s52
	s_addc_u32 s99, s99, s53
	s_lshl_b32 s100, s45, 15
	s_add_u32 s98, s98, s100
	s_addc_u32 s99, s99, 0
	v_readlane_b32 s100, v244, 25
	v_lshrrev_b32_e32 v190, 4, v144
	v_and_b32_e32 v191, 15, v144
	v_lshl_add_u32 v190, s100, 4, v190
	v_lshlrev_b32_e32 v190, 8, v190
	v_lshl_add_u32 v190, v191, 4, v190
	global_load_dwordx4 v[192:195], v190, s[98:99]
	global_load_dwordx4 v[196:199], v190, s[98:99] offset:1024
	global_load_dwordx4 v[232:235], v190, s[98:99] offset:2048
	global_load_dwordx4 v[236:239], v190, s[98:99] offset:3072
	s_waitcnt vmcnt(14)
	s_and_saveexec_b64 s[0:1], s[2:3]
	v_cvt_pk_bf16_f32 v16, v23, v16
	v_cvt_pk_bf16_f32 v17, v17, v18
	v_cvt_pk_bf16_f32 v18, v19, v24
	v_cvt_pk_bf16_f32 v19, v25, v26
